# v100 + P6 row-sum exchange: partial sums stored without write-through in placement-verified mode (the four partner workgroups share one L2)
# baseline (speedup 1.0000x reference)
; #define LAS __attribute__((address_space(3)))
;     __device__ __forceinline__ void fused(f32x4 (&acc)[2][2][4][2], const Unit& u, int wr, int wc, int fr, int fq, PG8_LAS unsigned char* lds, int wid, int lane) const {
;     ...
;         const int tid = wid * 64 + lane;
;         if (tid < 256) { const f32x4 p = *(const LAS f32x4*)(PS + tid * 4);
;             __hip_atomic_store(xbuf + (size_t)(u.pm * 256 + tid) * 4 + u.pn, (p[0] + p[1]) + (p[2] + p[3]), __ATOMIC_RELAXED, __HIP_MEMORY_SCOPE_AGENT); }
.LBB0_704:
	s_or_b64 exec, exec, s[2:3]
	s_add_u32 s2, s78, 0x1f10000
	s_addc_u32 s3, s79, 0
	s_andn2_b32 s9, s9, 63
	s_waitcnt lgkmcnt(0)
	s_barrier
	v_or_b32_e32 v2, s9, v157
	s_movk_i32 s0, 0x100
	v_add_u32_e32 v0, s12, v2
	v_cmp_gt_i32_e64 s[0:1], s0, v2
	s_waitcnt lgkmcnt(0)
	v_ashrrev_i32_e32 v1, 31, v0
	s_and_saveexec_b64 s[4:5], s[0:1]
	s_cbranch_execz .LBB0_706
	v_lshl_add_u32 v3, v2, 4, 0
	ds_read_b128 v[4:7], v3
	v_lshl_add_u64 v[8:9], v[0:1], 4, s[2:3]
	s_ashr_i32 s9, s8, 31
	v_lshl_add_u64 v[8:9], s[8:9], 2, v[8:9]
	s_waitcnt lgkmcnt(0)
	v_mov_b32_e32 v10, v5
	v_mov_b32_e32 v11, v6
	v_mov_b32_e32 v5, v7
	v_pk_add_f32 v[4:5], v[10:11], v[4:5]
	s_nop 0
	v_pk_add_f32 v[4:5], v[4:5], v[4:5] op_sel:[0,1] op_sel_hi:[1,0]
	v_mov_b32_e32 v12, 0x27e08
	ds_read_b32 v12, v12
	s_waitcnt lgkmcnt(0)
	v_readfirstlane_b32 s10, v12
	s_nop 3
	s_cmp_eq_u32 s10, 2
	s_cbranch_scc1 .Lx6_fast
	global_store_dword v[8:9], v4, off sc1
	s_branch .LBB0_706
.Lx6_fast:
	global_store_dword v[8:9], v4, off
